# o52: o51 + final RMSNorm loop prefetches two rows ahead (unrolled x2, vmcnt(12))
# baseline (speedup 1.0000x reference)
; __device__ __forceinline__ float hsq4(const f32x4& a) { return (a[0] * a[0] + a[1] * a[1]) + (a[2] * a[2] + a[3] * a[3]); }
; __device__ __forceinline__ void phase_final(int wid0, const pg8::Place& pl, const float* g, const bf16_t* xb, float* dst) {
;     ...
;     for (int lr = pl.rank * NWAVES + wave; lr < nr; lr += pl.nloc * NWAVES) { const int row = r0 + lr;
;         const pg8::u32x2* xr = (const pg8::u32x2*)(xb + (size_t)row * (2 * DM) + DM); f32x4* yr = (f32x4*)(dst + (size_t)row * DM); f32x4 v[4]; float s = 0.f;
; #pragma unroll
;         for (int j = 0; j < 4; ++j) { const pg8::u32x2 w = xr[lane + 64 * j];
;             v[j][0] = __uint_as_float(w.x << 16); v[j][1] = __uint_as_float(w.x & 0xffff0000u); v[j][2] = __uint_as_float(w.y << 16); v[j][3] = __uint_as_float(w.y & 0xffff0000u); s += pg8::hsq4(v[j]); }
;         const float rstd = rsqrtf(wsum(s) * (1.f / DM) + EPS);
; #pragma unroll
;         for (int j = 0; j < 4; ++j) yr[lane + 64 * j] = v[j] * rstd * *(const f32x4*)(g + 4 * (lane + 64 * j)); }
.LBB13_2253:
	global_load_dwordx4 v[44:47], v[0:1], off
	global_load_dwordx4 v[48:51], v[2:3], off
	global_load_dwordx4 v[52:55], v[4:5], off
	global_load_dwordx4 v[56:59], v[6:7], off
	v_lshl_add_u64 v[18:19], v[8:9], 0, s[2:3]
	global_load_dwordx2 v[60:61], v[18:19], off offset:2048
	global_load_dwordx2 v[62:63], v[18:19], off offset:2560
	global_load_dwordx2 v[64:65], v[18:19], off offset:3072
	global_load_dwordx2 v[66:67], v[18:19], off offset:3584
	v_lshl_add_u64 v[72:73], v[18:19], 0, s[4:5]
	s_add_i32 s14, s8, -8
	global_load_dwordx2 v[74:75], v[72:73], off offset:2048
	global_load_dwordx2 v[76:77], v[72:73], off offset:2560
	global_load_dwordx2 v[78:79], v[72:73], off offset:3072
	global_load_dwordx2 v[80:81], v[72:73], off offset:3584
	s_waitcnt vmcnt(0)
	s_branch .Lfin_bodyP
.Lfin_topP:
	s_waitcnt vmcnt(12)
.Lfin_bodyP:
	v_mov_b32_e32 v20, v60
	v_mov_b32_e32 v21, v61
	v_mov_b32_e32 v22, v62
	v_mov_b32_e32 v23, v63
	v_mov_b32_e32 v24, v64
	v_mov_b32_e32 v25, v65
	v_mov_b32_e32 v26, v66
	v_mov_b32_e32 v27, v67
	v_lshl_add_u64 v[18:19], v[10:11], 0, s[2:3]
	v_add_u32_e32 v12, s0, v12
	v_lshl_add_u64 v[8:9], v[8:9], 0, s[4:5]
	v_lshl_add_u64 v[10:11], v[10:11], 0, s[4:5]
	v_cmp_le_i32_e32 vcc, s8, v12
	s_or_b64 s[6:7], vcc, s[6:7]
	v_cmp_le_i32_e32 vcc, s14, v12
	s_cbranch_vccnz .Lfin_noloadP
	v_lshl_add_u64 v[72:73], v[8:9], 0, s[4:5]
	s_nop 0
	v_lshl_add_u64 v[72:73], v[72:73], 0, s[2:3]
	global_load_dwordx2 v[60:61], v[72:73], off offset:2048
	global_load_dwordx2 v[62:63], v[72:73], off offset:2560
	global_load_dwordx2 v[64:65], v[72:73], off offset:3072
	global_load_dwordx2 v[66:67], v[72:73], off offset:3584
	s_branch .Lfin_compP

; __device__ __forceinline__ float hsq4(const f32x4& a) { return (a[0] * a[0] + a[1] * a[1]) + (a[2] * a[2] + a[3] * a[3]); }
; __device__ __forceinline__ void phase_final(int wid0, const pg8::Place& pl, const float* g, const bf16_t* xb, float* dst) {
;     ...
;     for (int lr = pl.rank * NWAVES + wave; lr < nr; lr += pl.nloc * NWAVES) { const int row = r0 + lr;
;         const pg8::u32x2* xr = (const pg8::u32x2*)(xb + (size_t)row * (2 * DM) + DM); f32x4* yr = (f32x4*)(dst + (size_t)row * DM); f32x4 v[4]; float s = 0.f;
; #pragma unroll
;         for (int j = 0; j < 4; ++j) { const pg8::u32x2 w = xr[lane + 64 * j];
;             v[j][0] = __uint_as_float(w.x << 16); v[j][1] = __uint_as_float(w.x & 0xffff0000u); v[j][2] = __uint_as_float(w.y << 16); v[j][3] = __uint_as_float(w.y & 0xffff0000u); s += pg8::hsq4(v[j]); }
;         const float rstd = rsqrtf(wsum(s) * (1.f / DM) + EPS);
; #pragma unroll
;         for (int j = 0; j < 4; ++j) yr[lane + 64 * j] = v[j] * rstd * *(const f32x4*)(g + 4 * (lane + 64 * j)); }
.Lfin_compP:
	v_lshlrev_b32_e32 v28, 16, v20
	v_and_b32_e32 v29, 0xffff0000, v20
	v_lshlrev_b32_e32 v20, 16, v21
	v_lshlrev_b32_e32 v30, 16, v22
	v_and_b32_e32 v31, 0xffff0000, v22
	v_lshlrev_b32_e32 v22, 16, v23
	v_and_b32_e32 v21, 0xffff0000, v21
	v_and_b32_e32 v23, 0xffff0000, v23
	v_lshlrev_b32_e32 v32, 16, v24
	v_and_b32_e32 v33, 0xffff0000, v24
	v_lshlrev_b32_e32 v24, 16, v25
	v_mul_f32_e32 v36, v29, v29
	v_mul_f32_e32 v37, v20, v20
	v_mul_f32_e32 v38, v31, v31
	v_mul_f32_e32 v39, v22, v22
	v_and_b32_e32 v25, 0xffff0000, v25
	v_lshlrev_b32_e32 v34, 16, v26
	v_and_b32_e32 v35, 0xffff0000, v26
	v_lshlrev_b32_e32 v26, 16, v27
	v_mul_f32_e32 v40, v33, v33
	v_mul_f32_e32 v41, v24, v24
	v_fmac_f32_e32 v36, v28, v28
	v_fmac_f32_e32 v37, v21, v21
	v_fmac_f32_e32 v38, v30, v30
	v_fmac_f32_e32 v39, v23, v23
	v_and_b32_e32 v27, 0xffff0000, v27
	v_mul_f32_e32 v42, v35, v35
	v_mul_f32_e32 v43, v26, v26
	v_fmac_f32_e32 v40, v32, v32
	v_fmac_f32_e32 v41, v25, v25
	v_add_f32_e32 v36, v36, v37
	v_add_f32_e32 v37, v38, v39
	v_fmac_f32_e32 v42, v34, v34
	v_fmac_f32_e32 v43, v27, v27
	v_add_f32_e32 v38, v40, v41
	v_add_f32_e32 v36, v36, v37
	v_add_f32_e32 v39, v42, v43
	v_add_f32_e32 v36, v36, v38
	v_add_f32_e32 v36, v36, v39
	ds_swizzle_b32 v37, v36 offset:swizzle(SWAP,1)
	s_waitcnt lgkmcnt(0)
	v_add_f32_e32 v36, v36, v37
	ds_swizzle_b32 v37, v36 offset:swizzle(SWAP,2)
	s_waitcnt lgkmcnt(0)
	v_add_f32_e32 v36, v36, v37
	ds_swizzle_b32 v37, v36 offset:swizzle(SWAP,4)
	s_waitcnt lgkmcnt(0)
	v_add_f32_e32 v36, v36, v37
	ds_swizzle_b32 v37, v36 offset:swizzle(SWAP,8)
	s_waitcnt lgkmcnt(0)
	v_add_f32_e32 v36, v36, v37
	ds_swizzle_b32 v37, v36 offset:swizzle(SWAP,16)
	s_waitcnt lgkmcnt(0)
	v_add_f32_e32 v36, v36, v37
	v_mov_b32_e32 v37, v36
	s_nop 1
	v_permlane32_swap_b32_e32 v36, v37
	v_add_f32_e32 v36, v36, v37
	v_fmamk_f32 v36, v36, 0x3a800000, v13
	v_mul_f32_e32 v37, 0x4b800000, v36
	v_cmp_gt_f32_e32 vcc, s1, v36
	s_nop 1
	v_cndmask_b32_e32 v36, v36, v37, vcc
	v_rsq_f32_e32 v36, v36
	s_nop 0
	v_mul_f32_e32 v37, 0x45800000, v36
	v_cndmask_b32_e32 v36, v36, v37, vcc
	v_pk_mul_f32 v[28:29], v[28:29], v[36:37] op_sel_hi:[1,0]
	v_pk_mul_f32 v[20:21], v[20:21], v[36:37] op_sel_hi:[1,0]
	v_pk_mul_f32 v[14:15], v[44:45], v[28:29]
	v_pk_mul_f32 v[16:17], v[46:47], v[20:21]
	global_store_dwordx4 v[18:19], v[14:17], off
	v_pk_mul_f32 v[20:21], v[22:23], v[36:37] op_sel_hi:[1,0]
	v_pk_mul_f32 v[22:23], v[30:31], v[36:37] op_sel_hi:[1,0]
	v_pk_mul_f32 v[68:69], v[48:49], v[22:23]
	v_pk_mul_f32 v[70:71], v[50:51], v[20:21]
	global_store_dwordx4 v[18:19], v[68:71], off offset:1024
	v_pk_mul_f32 v[20:21], v[24:25], v[36:37] op_sel_hi:[1,0]
	v_pk_mul_f32 v[22:23], v[32:33], v[36:37] op_sel_hi:[1,0]
	v_pk_mul_f32 v[16:17], v[54:55], v[20:21]
	v_pk_mul_f32 v[14:15], v[52:53], v[22:23]
	global_store_dwordx4 v[18:19], v[14:17], off offset:2048
	v_pk_mul_f32 v[20:21], v[26:27], v[36:37] op_sel_hi:[1,0]
	v_pk_mul_f32 v[22:23], v[34:35], v[36:37] op_sel_hi:[1,0]
	v_pk_mul_f32 v[70:71], v[58:59], v[20:21]
	v_pk_mul_f32 v[68:69], v[56:57], v[22:23]
	global_store_dwordx4 v[18:19], v[68:71], off offset:3072
	s_andn2_b64 exec, exec, s[6:7]
	s_cbranch_execz .Lfin_end

; __device__ __forceinline__ float hsq4(const f32x4& a) { return (a[0] * a[0] + a[1] * a[1]) + (a[2] * a[2] + a[3] * a[3]); }
; __device__ __forceinline__ void phase_final(int wid0, const pg8::Place& pl, const float* g, const bf16_t* xb, float* dst) {
;     ...
;     for (int lr = pl.rank * NWAVES + wave; lr < nr; lr += pl.nloc * NWAVES) { const int row = r0 + lr;
;         const pg8::u32x2* xr = (const pg8::u32x2*)(xb + (size_t)row * (2 * DM) + DM); f32x4* yr = (f32x4*)(dst + (size_t)row * DM); f32x4 v[4]; float s = 0.f;
; #pragma unroll
;         for (int j = 0; j < 4; ++j) { const pg8::u32x2 w = xr[lane + 64 * j];
;             v[j][0] = __uint_as_float(w.x << 16); v[j][1] = __uint_as_float(w.x & 0xffff0000u); v[j][2] = __uint_as_float(w.y << 16); v[j][3] = __uint_as_float(w.y & 0xffff0000u); s += pg8::hsq4(v[j]); }
;         const float rstd = rsqrtf(wsum(s) * (1.f / DM) + EPS);
; #pragma unroll
;         for (int j = 0; j < 4; ++j) yr[lane + 64 * j] = v[j] * rstd * *(const f32x4*)(g + 4 * (lane + 64 * j)); }
.Lfin_bodyQ:
	v_mov_b32_e32 v20, v74
	v_mov_b32_e32 v21, v75
	v_mov_b32_e32 v22, v76
	v_mov_b32_e32 v23, v77
	v_mov_b32_e32 v24, v78
	v_mov_b32_e32 v25, v79
	v_mov_b32_e32 v26, v80
	v_mov_b32_e32 v27, v81
	v_lshl_add_u64 v[18:19], v[10:11], 0, s[2:3]
	v_add_u32_e32 v12, s0, v12
	v_lshl_add_u64 v[8:9], v[8:9], 0, s[4:5]
	v_lshl_add_u64 v[10:11], v[10:11], 0, s[4:5]
	v_cmp_le_i32_e32 vcc, s8, v12
	s_or_b64 s[6:7], vcc, s[6:7]
	v_cmp_le_i32_e32 vcc, s14, v12
	s_cbranch_vccnz .Lfin_noloadQ
	v_lshl_add_u64 v[72:73], v[8:9], 0, s[4:5]
	s_nop 0
	v_lshl_add_u64 v[72:73], v[72:73], 0, s[2:3]
	global_load_dwordx2 v[74:75], v[72:73], off offset:2048
	global_load_dwordx2 v[76:77], v[72:73], off offset:2560
	global_load_dwordx2 v[78:79], v[72:73], off offset:3072
	global_load_dwordx2 v[80:81], v[72:73], off offset:3584
	s_branch .Lfin_compQ
.Lfin_noloadQ:
	s_waitcnt vmcnt(0)
.Lfin_compQ:
	v_lshlrev_b32_e32 v28, 16, v20
	v_and_b32_e32 v29, 0xffff0000, v20
	v_lshlrev_b32_e32 v20, 16, v21
	v_lshlrev_b32_e32 v30, 16, v22
	v_and_b32_e32 v31, 0xffff0000, v22
	v_lshlrev_b32_e32 v22, 16, v23
	v_and_b32_e32 v21, 0xffff0000, v21
	v_and_b32_e32 v23, 0xffff0000, v23
	v_lshlrev_b32_e32 v32, 16, v24
	v_and_b32_e32 v33, 0xffff0000, v24
	v_lshlrev_b32_e32 v24, 16, v25
	v_mul_f32_e32 v36, v29, v29
	v_mul_f32_e32 v37, v20, v20
	v_mul_f32_e32 v38, v31, v31
	v_mul_f32_e32 v39, v22, v22
	v_and_b32_e32 v25, 0xffff0000, v25
	v_lshlrev_b32_e32 v34, 16, v26
	v_and_b32_e32 v35, 0xffff0000, v26
	v_lshlrev_b32_e32 v26, 16, v27
	v_mul_f32_e32 v40, v33, v33
	v_mul_f32_e32 v41, v24, v24
	v_fmac_f32_e32 v36, v28, v28
	v_fmac_f32_e32 v37, v21, v21
	v_fmac_f32_e32 v38, v30, v30
	v_fmac_f32_e32 v39, v23, v23
	v_and_b32_e32 v27, 0xffff0000, v27
	v_mul_f32_e32 v42, v35, v35
	v_mul_f32_e32 v43, v26, v26
	v_fmac_f32_e32 v40, v32, v32
	v_fmac_f32_e32 v41, v25, v25
	v_add_f32_e32 v36, v36, v37
	v_add_f32_e32 v37, v38, v39
	v_fmac_f32_e32 v42, v34, v34
	v_fmac_f32_e32 v43, v27, v27
	v_add_f32_e32 v38, v40, v41
	v_add_f32_e32 v36, v36, v37
	v_add_f32_e32 v39, v42, v43
	v_add_f32_e32 v36, v36, v38
	v_add_f32_e32 v36, v36, v39
	ds_swizzle_b32 v37, v36 offset:swizzle(SWAP,1)
	s_waitcnt lgkmcnt(0)
	v_add_f32_e32 v36, v36, v37
	ds_swizzle_b32 v37, v36 offset:swizzle(SWAP,2)
	s_waitcnt lgkmcnt(0)
	v_add_f32_e32 v36, v36, v37
	ds_swizzle_b32 v37, v36 offset:swizzle(SWAP,4)
	s_waitcnt lgkmcnt(0)
	v_add_f32_e32 v36, v36, v37
	ds_swizzle_b32 v37, v36 offset:swizzle(SWAP,8)
	s_waitcnt lgkmcnt(0)
	v_add_f32_e32 v36, v36, v37
	ds_swizzle_b32 v37, v36 offset:swizzle(SWAP,16)
	s_waitcnt lgkmcnt(0)
	v_add_f32_e32 v36, v36, v37
	v_mov_b32_e32 v37, v36
	s_nop 1
	v_permlane32_swap_b32_e32 v36, v37
	v_add_f32_e32 v36, v36, v37
	v_fmamk_f32 v36, v36, 0x3a800000, v13
	v_mul_f32_e32 v37, 0x4b800000, v36
	v_cmp_gt_f32_e32 vcc, s1, v36
	s_nop 1
	v_cndmask_b32_e32 v36, v36, v37, vcc
	v_rsq_f32_e32 v36, v36
	s_nop 0
	v_mul_f32_e32 v37, 0x45800000, v36
	v_cndmask_b32_e32 v36, v36, v37, vcc
	v_pk_mul_f32 v[28:29], v[28:29], v[36:37] op_sel_hi:[1,0]
	v_pk_mul_f32 v[20:21], v[20:21], v[36:37] op_sel_hi:[1,0]
	v_pk_mul_f32 v[14:15], v[44:45], v[28:29]
	v_pk_mul_f32 v[16:17], v[46:47], v[20:21]
	global_store_dwordx4 v[18:19], v[14:17], off
	v_pk_mul_f32 v[20:21], v[22:23], v[36:37] op_sel_hi:[1,0]
	v_pk_mul_f32 v[22:23], v[30:31], v[36:37] op_sel_hi:[1,0]
	v_pk_mul_f32 v[68:69], v[48:49], v[22:23]
	v_pk_mul_f32 v[70:71], v[50:51], v[20:21]
	global_store_dwordx4 v[18:19], v[68:71], off offset:1024
	v_pk_mul_f32 v[20:21], v[24:25], v[36:37] op_sel_hi:[1,0]
	v_pk_mul_f32 v[22:23], v[32:33], v[36:37] op_sel_hi:[1,0]
	v_pk_mul_f32 v[16:17], v[54:55], v[20:21]
	v_pk_mul_f32 v[14:15], v[52:53], v[22:23]
	global_store_dwordx4 v[18:19], v[14:17], off offset:2048
	v_pk_mul_f32 v[20:21], v[26:27], v[36:37] op_sel_hi:[1,0]
	v_pk_mul_f32 v[22:23], v[34:35], v[36:37] op_sel_hi:[1,0]
	v_pk_mul_f32 v[70:71], v[58:59], v[20:21]
	v_pk_mul_f32 v[68:69], v[56:57], v[22:23]
	global_store_dwordx4 v[18:19], v[68:71], off offset:3072
	s_andn2_b64 exec, exec, s[6:7]
	s_cbranch_execnz .Lfin_topP
.Lfin_end:
.LBB13_2254:
	s_endpgm
